# scan loops (gdn+mlstm): per-chunk prefetch loads spread across the next chunk's MFMA stream, dedicated address registers, uniform counted vmcnt
# speedup vs baseline: 1.0363x; 1.0106x over previous
.LBB0_433:
	s_or_b64 exec, exec, s[0:1]
	s_mov_b32 s0, 0x3fb8aa3b
	s_waitcnt vmcnt(6)
	v_mul_f32_e64 v59, -v66, s0
	s_waitcnt lgkmcnt(6)
	v_add_f32_e32 v177, v66, v67
	global_load_dwordx4 v[64:67], v[64:65], off offset:2048
	s_bfe_u32 s1, s66, 0x30001
	s_lshr_b32 s10, s58, 6
	s_lshl_b32 s0, s1, 21
	s_lshl_b32 s11, s10, 20
	s_add_i32 s72, s0, s11
	s_lshl_b32 s0, s1, 1
	s_waitcnt vmcnt(0)
	v_ashrrev_i32_e32 v67, 7, v74
	v_lshlrev_b32_e32 v100, 1, v82
	v_exp_f32_e32 v114, v59
	v_lshrrev_b32_e32 v59, 4, v75
	s_lshl_b32 s91, s1, 14
	s_lshl_b32 s3, s10, 13
	s_add_i32 s0, s10, s0
	s_lshl_b32 s1, s1, 17
	s_lshl_b32 s10, s10, 16
	v_and_b32_e32 v104, 2, v100
	v_lshlrev_b32_e32 v100, 4, v67
	v_and_b32_e32 v73, 15, v74
	s_add_i32 s1, s1, s10
	s_and_b32 s10, s2, 7
	v_lshl_or_b32 v105, v59, 2, v100
	v_lshlrev_b32_e32 v101, 5, v67
	v_lshlrev_b32_e32 v59, 3, v59
	v_readlane_b32 s12, v250, 54
	v_and_b32_e32 v106, 48, v75
	s_lshl_b32 s10, s10, 13
	v_bfe_u32 v83, v74, 6, 1
	v_add3_u32 v117, s12, v101, v59
	v_or_b32_e32 v102, v100, v73
	v_add_u32_e32 v116, 0, v106
	s_lshl_b64 s[92:93], s[72:73], 1
	s_or_b32 s72, s1, s10
	v_mad_u64_u32 v[100:101], s[10:11], v102, s25, v[116:117]
	v_lshl_or_b32 v103, v83, 4, v73
	v_mul_lo_u32 v102, v102, s33
	v_add3_u32 v127, s12, v102, v106
	v_mul_u32_u24_e32 v102, 0x90, v103
	v_add3_u32 v128, s65, v102, v106
	v_lshl_or_b32 v102, v82, 4, v73
	v_mad_u32_u24 v101, v103, s25, v116
	v_mad_u64_u32 v[102:103], s[10:11], v102, s33, v[116:117]
	v_and_or_b32 v74, v74, 48, v80
	v_lshlrev_b32_e32 v131, 2, v74
	v_lshlrev_b32_e32 v74, 5, v83
	v_lshlrev_b32_e32 v83, 1, v73
	v_readlane_b32 s10, v250, 55
	s_movk_i32 s18, 0x50
	v_lshlrev_b32_e32 v110, 4, v78
	v_add3_u32 v74, s10, v74, v83
	v_mul_lo_u32 v83, v92, s18
	v_add3_u32 v134, s10, v83, v110
	v_cmp_eq_u32_e64 s[10:11], 0, v78
	v_mul_lo_u32 v120, v105, s18
	v_cmp_gt_u32_e64 s[18:19], 2, v78
	v_or_b32_e32 v78, v77, v76
	v_mul_u32_u24_e32 v78, 0x48, v78
	v_lshlrev_b32_e32 v82, 5, v82
	v_add_lshl_u32 v78, v92, v78, 1
	v_add3_u32 v59, 0, v82, v59
	v_lshlrev_b32_e32 v82, 2, v75
	s_add_i32 s48, 0, 0x17200
	s_add_i32 s14, 0, 0x17100
	s_add_i32 s16, 0, 0x17400
	s_add_i32 s17, 0, 0x17300
	v_add_u32_e32 v148, s65, v78
	v_add_u32_e32 v149, s64, v78
	v_add_u32_e32 v78, 0x90, v78
	v_add_u32_e32 v132, s48, v82
	v_add_u32_e32 v133, s14, v82
	v_add_u32_e32 v137, s16, v82
	v_add_u32_e32 v138, s17, v82
	v_lshlrev_b32_e32 v82, 2, v105
	v_add_u32_e32 v150, s65, v78
	v_add_u32_e32 v151, s64, v78
	v_add_u32_e32 v78, 2, v77
	v_add_u32_e32 v146, s17, v82
	v_add_u32_e32 v147, s16, v82
	v_cmp_eq_u32_e64 s[16:17], 0, v79
	v_and_b32_e32 v79, 4, v78
	v_and_or_b32 v78, v78, 6, v76
	v_mul_u32_u24_e32 v78, 0x48, v78
	v_add_lshl_u32 v78, v92, v78, 1
	v_add_u32_e32 v152, s65, v78
	v_add_u32_e32 v153, s64, v78
	v_add_u32_e32 v78, 3, v77
	v_cmp_eq_u32_e64 s[20:21], 0, v79
	v_and_b32_e32 v79, 2, v78
	v_cmp_eq_u32_e64 s[22:23], 0, v79
	v_and_b32_e32 v79, 4, v78
	v_and_or_b32 v78, v78, 7, v76
	v_mul_u32_u24_e32 v78, 0x48, v78
	v_mul_u32_u24_e32 v129, 0x90, v73
	v_add_lshl_u32 v78, v92, v78, 1
	v_add3_u32 v130, s65, v129, v106
	v_add_u32_e32 v254, s65, v106
	v_add_u32_e32 v103, s64, v106
	v_xor_b32_e32 v83, 1, v123
	v_add_u32_e32 v106, 64, v80
	v_add_u32_e32 v154, s65, v78
	v_add_u32_e32 v155, s64, v78
	v_bitop3_b32 v78, v77, 4, v76 bitop3:0x36
	v_cmp_lt_i32_e32 vcc, v83, v106
	v_mul_u32_u24_e32 v78, 0x48, v78
	v_add_lshl_u32 v78, v92, v78, 1
	v_cndmask_b32_e32 v83, v123, v83, vcc
	v_lshlrev_b32_e32 v135, 2, v83
	v_xor_b32_e32 v83, 2, v123
	v_add_u32_e32 v156, s65, v78
	v_add_u32_e32 v157, s64, v78
	v_add_u32_e32 v78, 5, v77
	v_mad_u32_u24 v115, v73, s25, v116
	v_mov_b32_e32 v253, v116
	v_cmp_lt_i32_e32 vcc, v83, v106
	v_cmp_eq_u32_e64 s[24:25], 0, v79
	v_and_b32_e32 v79, 2, v78
	v_cndmask_b32_e32 v83, v123, v83, vcc
	v_and_or_b32 v80, v92, 63, v80
	v_cmp_eq_u32_e64 s[26:27], 0, v79
	v_and_b32_e32 v79, 4, v78
	v_and_or_b32 v78, v78, 7, v76
	s_lshl_b32 s0, s0, 10
	v_lshlrev_b32_e32 v136, 2, v83
	v_lshlrev_b32_e32 v139, 2, v80
	v_cmp_le_i32_e64 s[12:13], v67, v104
	v_lshl_or_b32 v80, v104, 4, v73
	v_or_b32_e32 v83, 2, v105
	v_or_b32_e32 v106, 3, v105
	v_or_b32_e32 v104, 1, v104
	v_mul_u32_u24_e32 v78, 0x48, v78
	s_and_b32 s0, s0, 0xffffe000
	s_mov_b32 s1, s73
	v_add_u32_e32 v142, s14, v82
	v_lshl_add_u32 v144, v83, 2, s14
	v_lshl_add_u32 v145, v106, 2, s14
	v_cmp_le_i32_e64 s[14:15], v67, v104
	v_lshl_or_b32 v67, v104, 4, v73
	v_add_lshl_u32 v78, v92, v78, 1
	v_add_u32_e32 v158, s65, v78
	v_add_u32_e32 v159, s64, v78
	v_add_u32_e32 v78, 6, v77
	v_cmp_le_i32_e64 s[46:47], v106, v80
	v_cmp_le_i32_e64 s[54:55], v106, v67
	v_lshl_add_u64 v[106:107], v[68:69], 1, s[92:93]
	v_lshl_add_u64 v[68:69], v[92:93], 0, s[0:1]
	v_cmp_eq_u32_e64 s[28:29], 0, v79
	v_and_b32_e32 v79, 2, v78
	v_lshl_add_u32 v166, v80, 2, s48
	v_cmp_le_i32_e64 s[40:41], v105, v80
	v_cmp_lt_i32_e64 s[42:43], v105, v80
	v_lshl_add_u32 v167, v67, 2, s48
	v_cmp_le_i32_e64 s[48:49], v105, v67
	v_cmp_lt_i32_e64 s[50:51], v105, v67
	v_lshl_add_u64 v[104:105], v[70:71], 1, s[92:93]
	v_mad_u64_u32 v[70:71], s[92:93], v68, s96, 0
	v_cmp_eq_u32_e64 s[30:31], 0, v79
	v_and_b32_e32 v79, 4, v78
	v_and_or_b32 v78, v78, 6, v76
	v_add_u32_e32 v77, 7, v77
	v_mov_b32_e32 v68, v71
	v_mul_u32_u24_e32 v78, 0x48, v78
	v_and_or_b32 v76, v77, 7, v76
	v_mad_u64_u32 v[68:69], s[92:93], v69, s96, v[68:69]
	v_add_lshl_u32 v78, v92, v78, 1
	v_mul_u32_u24_e32 v76, 0x48, v76
	v_or_b32_e32 v70, v70, v110
	v_mov_b32_e32 v71, v68
	v_mul_u32_u24_e32 v118, 0x110, v73
	v_or_b32_e32 v73, 16, v73
	v_add_u32_e32 v160, s65, v78
	v_add_u32_e32 v161, s64, v78
	v_and_b32_e32 v78, 2, v77
	v_add_lshl_u32 v76, v92, v76, 1
	v_lshl_add_u64 v[68:69], v[98:99], 1, v[70:71]
	v_lshlrev_b32_e32 v110, 1, v72
	v_mov_b32_e32 v111, v85
	s_lshl_b64 s[94:95], s[72:73], 2
	v_add_u32_e32 v140, s64, v81
	v_add_u32_e32 v141, s65, v81
	v_mul_u32_u24_e32 v81, 0x110, v80
	v_mul_u32_u24_e32 v119, 0x110, v67
	v_mul_u32_u24_e32 v82, 0x90, v73
	v_mul_u32_u24_e32 v73, 0x110, v73
	v_cmp_eq_u32_e64 s[36:37], 0, v78
	v_and_b32_e32 v78, 4, v77
	v_add_u32_e32 v162, s65, v76
	v_add_u32_e32 v163, s64, v76
	v_mul_u32_u24_e32 v76, 0x90, v80
	v_cmp_le_i32_e64 s[52:53], v83, v67
	v_mul_u32_u24_e32 v67, 0x90, v67
	s_add_i32 s91, s91, s3
	v_lshl_add_u64 v[112:113], v[68:69], 0, v[110:111]
	v_mov_b32_e32 v68, 0
	s_mov_b32 s62, 0
	v_add_u32_e32 v143, 4, v142
	v_cmp_eq_u32_e64 s[34:35], 0, v79
	v_cmp_eq_u32_e64 s[38:39], 0, v78
	v_cmp_le_i32_e64 s[44:45], v83, v80
	v_or_b32_e32 v168, s91, v75
	v_lshl_add_u64 v[108:109], v[92:93], 2, s[94:95]
	v_add_u32_e32 v169, v116, v81
	v_add_u32_e32 v170, v117, v76
	v_add_u32_e32 v171, v116, v119
	v_add_u32_e32 v172, v117, v67
	v_add_u32_e32 v173, v103, v82
	v_add_u32_e32 v174, v74, v120
	v_add_u32_e32 v175, v59, v118
	v_add_u32_e32 v176, v59, v73
	s_mov_b32 s1, 0
	v_mov_b32_e32 v69, v68
	v_mov_b32_e32 v70, v68
	v_mov_b32_e32 v71, v68
	v_mov_b32_e32 v72, v68
	v_mov_b32_e32 v73, v68
	v_mov_b32_e32 v74, v68
	v_mov_b32_e32 v75, v68
	v_mov_b32_e32 v76, v68
	v_mov_b32_e32 v77, v68
	v_mov_b32_e32 v78, v68
	v_mov_b32_e32 v79, v68
	s_waitcnt lgkmcnt(0)
	s_barrier
	s_mov_b32 s98, 0x180000
	s_mov_b32 s99, 0
	s_mov_b32 s100, 0x4000
	s_mov_b32 s101, 0
	s_add_i32 s3, s0, s62
	s_add_i32 s72, s3, 0x80
	s_mov_b32 s91, s73
	v_mov_b64_e32 v[2:3], s[68:69]
	v_lshl_add_u64 v[240:241], s[72:73], 0, v[86:87]
	v_mad_u64_u32 v[244:245], s[92:93], v240, s96, v[2:3]
	v_mad_i32_i24 v245, v241, s96, v245
	v_lshl_add_u64 v[240:241], v[244:245], 0, s[90:91]
	v_lshl_add_u64 v[240:241], v[240:241], 0, v[84:85]
	v_add_co_u32_e32 v240, vcc, 0x4000, v240
	s_nop 1
	v_addc_co_u32_e32 v241, vcc, 0, v241, vcc
	v_lshl_add_u64 v[244:245], s[72:73], 0, v[88:89]
	v_mad_u64_u32 v[246:247], s[92:93], v244, s96, v[2:3]
	v_mad_i32_i24 v247, v245, s96, v247
	v_lshl_add_u64 v[244:245], v[246:247], 0, s[90:91]
	v_lshl_add_u64 v[244:245], v[244:245], 0, v[84:85]
	v_add_co_u32_e32 v244, vcc, 0x4000, v244
	s_nop 1
	v_addc_co_u32_e32 v245, vcc, 0, v245, vcc
	v_lshl_add_u64 v[242:243], s[82:83], 0, v[106:107]
	v_add_co_u32_e32 v242, vcc, 0x8000, v242
	s_nop 1
	v_addc_co_u32_e32 v243, vcc, 0, v243, vcc
	v_lshl_add_u64 v[246:247], s[82:83], 0, v[104:105]
	v_add_co_u32_e32 v246, vcc, 0x8000, v246
	s_nop 1
	v_addc_co_u32_e32 v247, vcc, 0, v247, vcc
	v_lshl_add_u64 v[248:249], v[92:93], 0, s[72:73]
	v_mad_u64_u32 v[2:3], s[94:95], v248, s96, v[2:3]
	v_mov_b32_e32 v248, v3
	v_mad_u64_u32 v[248:249], s[94:95], v249, s96, v[248:249]
	v_mov_b32_e32 v3, v248
	v_lshl_add_u64 v[248:249], v[98:99], 1, v[2:3]
	v_mov_b32_e32 v111, v85
	v_lshl_add_u64 v[248:249], v[248:249], 0, v[110:111]
	v_lshl_add_u64 v[248:249], v[90:91], 1, v[248:249]
	v_add_co_u32_e32 v248, vcc, 0x5000, v248
	s_nop 1
	v_addc_co_u32_e32 v249, vcc, 0, v249, vcc
	v_add_u32_e32 v0, s62, v168
	v_add_u32_e32 v0, 0x80, v0
	v_mov_b32_e32 v1, v85
	v_lshl_add_u64 v[0:1], v[0:1], 4, s[70:71]
	s_branch .LBB0_436

.LBB0_438:
	s_or_b64 exec, exec, s[92:93]
	global_load_dwordx4 v[64:67], v[0:1], off
	v_add_co_u32_e32 v0, vcc, 0x400, v0
	s_nop 1
	v_addc_co_u32_e32 v1, vcc, 0, v1, vcc
	ds_read_b32 v111, v166
	v_mov_b32_e32 v251, 0
	v_mov_b32_e32 v252, 0
	s_and_saveexec_b64 s[92:93], s[40:41]
	s_cbranch_execz .LBB0_440
	ds_read_b32 v252, v142
	s_waitcnt lgkmcnt(0)
	v_sub_f32_e32 v252, v252, v111
	v_min_f32_e32 v252, 0, v252
	v_mul_f32_e32 v252, 0x3fb8aa3b, v252
	v_exp_f32_e32 v252, v252
	s_nop 0
	v_mul_f32_e32 v252, v80, v252
	v_cvt_pk_bf16_f32 v252, v252, s0

.LBB0_446:
	s_or_b64 exec, exec, s[92:93]
	global_load_dwordx4 v[32:35], v[240:241], off
	global_load_dwordx4 v[36:39], v[240:241], off offset:2048
	v_lshl_add_u64 v[240:241], v[240:241], 0, s[98:99]
	v_perm_b32 v82, v251, v252, s97
	v_perm_b32 v83, v80, v81, s97
	ds_write_b64 v170, v[82:83]
	v_mov_b32_e32 v251, 0
	v_mov_b32_e32 v80, 0
	v_mov_b32_e32 v81, 0
	v_mov_b32_e32 v82, 0
	v_mov_b32_e32 v83, 0
	s_and_saveexec_b64 s[92:93], s[14:15]
	s_cbranch_execz .LBB0_448
	ds_read_b128 v[80:83], v100 offset:17408
	ds_read_b128 v[116:119], v100 offset:17472
	ds_read_b128 v[178:181], v171
	ds_read_b128 v[182:185], v171 offset:64
	s_waitcnt lgkmcnt(1)
	v_mfma_f32_16x16x32_bf16 v[80:83], v[80:83], v[178:181], 0
	ds_read_b128 v[178:181], v100 offset:17536
	ds_read_b128 v[186:189], v100 offset:17600
	s_waitcnt lgkmcnt(2)
	v_mfma_f32_16x16x32_bf16 v[80:83], v[116:119], v[182:185], v[80:83]
	ds_read_b128 v[116:119], v171 offset:128
	ds_read_b128 v[182:185], v171 offset:192
	s_waitcnt lgkmcnt(1)
	v_mfma_f32_16x16x32_bf16 v[80:83], v[178:181], v[116:119], v[80:83]
	s_waitcnt lgkmcnt(0)
	v_mfma_f32_16x16x32_bf16 v[80:83], v[186:189], v[182:185], v[80:83]
.LBB0_448:
	s_or_b64 exec, exec, s[92:93]
	global_load_dwordx4 v[44:47], v[244:245], off
	global_load_dwordx4 v[48:51], v[244:245], off offset:2048
	v_lshl_add_u64 v[244:245], v[244:245], 0, s[98:99]
	ds_read_b32 v252, v167
	s_and_saveexec_b64 s[92:93], s[48:49]
	s_cbranch_execz .LBB0_450
	ds_read_b32 v251, v142
	s_waitcnt lgkmcnt(0)
	v_sub_f32_e32 v251, v251, v252
	v_min_f32_e32 v251, 0, v251
	v_mul_f32_e32 v251, 0x3fb8aa3b, v251
	v_exp_f32_e32 v251, v251
	s_nop 0
	v_mul_f32_e32 v251, v80, v251
	v_cvt_pk_bf16_f32 v251, v251, s0

.LBB0_454:
	s_or_b64 exec, exec, s[92:93]
	v_perm_b32 v82, v111, v251, s97
	v_perm_b32 v83, v81, v80, s97
	ds_write_b64 v172, v[82:83]
	ds_read_b128 v[80:83], v100
	ds_read_b128 v[116:119], v101 offset:34816
	ds_read_b128 v[178:181], v100 offset:64
	ds_read_b128 v[182:185], v101 offset:34880
	ds_read_b128 v[186:189], v253 offset:43520
	ds_read_b128 v[190:193], v253 offset:43584
	s_waitcnt lgkmcnt(4)
	v_mfma_f32_16x16x32_bf16 v[116:119], v[80:83], v[116:119], 0
	v_mul_f32_e64 v70, v70, v114
	v_mul_f32_e64 v71, v71, v114
	v_pk_mul_f32 v[68:69], v[68:69], v[114:115] op_sel_hi:[1,0]
	v_pk_mul_f32 v[78:79], v[78:79], v[114:115] op_sel_hi:[1,0]
	s_waitcnt lgkmcnt(2)
	v_mfma_f32_16x16x32_bf16 v[116:119], v[178:181], v[182:185], v[116:119]
	ds_read_b128 v[182:185], v100 offset:128
	v_pk_mul_f32 v[76:77], v[76:77], v[114:115] op_sel_hi:[1,0]
	v_pk_mul_f32 v[74:75], v[74:75], v[114:115] op_sel_hi:[1,0]
	s_waitcnt lgkmcnt(2)
	v_mfma_f32_16x16x32_bf16 v[80:83], v[80:83], v[186:189], 0
	v_mul_f32_e64 v72, v72, v114
	v_mul_f32_e64 v73, v73, v114
	s_waitcnt lgkmcnt(1)
	v_mfma_f32_16x16x32_bf16 v[80:83], v[178:181], v[190:193], v[80:83]
	ds_read_b128 v[178:181], v101 offset:34944
	ds_read_b128 v[186:189], v100 offset:192
	ds_read_b128 v[190:193], v101 offset:35008
	s_waitcnt lgkmcnt(2)
	v_mfma_f32_16x16x32_bf16 v[116:119], v[182:185], v[178:181], v[116:119]
	ds_read_b128 v[178:181], v253 offset:43648
	ds_read_b128 v[194:197], v253 offset:43712
	s_waitcnt lgkmcnt(0)
	s_barrier
	v_mfma_f32_16x16x32_bf16 v[80:83], v[182:185], v[178:181], v[80:83]
	ds_read_b128 v[178:181], v146
	ds_read_b128 v[182:185], v147
	v_mfma_f32_16x16x32_bf16 v[80:83], v[186:189], v[194:197], v[80:83]
	s_waitcnt lgkmcnt(0)
	v_max_f32_e32 v252, v182, v182
	v_mfma_f32_16x16x32_bf16 v[116:119], v[186:189], v[190:193], v[116:119]
	ds_read_b128 v[186:189], v127
	ds_read_b128 v[190:193], v127 offset:64
	ds_read_b128 v[194:197], v128
	ds_read_b128 v[198:201], v128 offset:64
	ds_read_b128 v[202:205], v254 offset:4608
	ds_read_b128 v[206:209], v254 offset:4672
	v_pk_mul_f32 v[82:83], v[82:83], v[180:181]
	v_pk_mul_f32 v[80:81], v[80:81], v[178:179]
	v_pk_mul_f32 v[118:119], v[118:119], v[180:181]
	v_pk_mul_f32 v[116:117], v[116:117], v[178:179]
	s_waitcnt lgkmcnt(1)
	v_mfma_f32_16x16x32_bf16 v[80:83], v[186:189], v[202:205], v[80:83]
	v_add_u32_e32 v180, v103, v129
	ds_read_b128 v[202:205], v102 offset:47872
	ds_read_b128 v[210:213], v102 offset:47936
	ds_read_b128 v[214:217], v180
	ds_read_b128 v[218:221], v180 offset:64
	s_waitcnt vmcnt(7)
	ds_bpermute_b32 v182, v124, v56
	s_waitcnt lgkmcnt(5)
	v_mfma_f32_16x16x32_bf16 v[80:83], v[190:193], v[206:209], v[80:83]
	global_load_dwordx4 v[40:43], v[242:243], off
	v_lshl_add_u64 v[242:243], v[242:243], 0, s[100:101]
	ds_read_b128 v[206:209], v173
	ds_read_b128 v[222:225], v173 offset:64
	ds_read_b128 v[226:229], v173 offset:2304
	ds_read_b128 v[230:233], v173 offset:2368
	v_mfma_f32_16x16x32_bf16 v[116:119], v[186:189], v[194:197], v[116:119]
	s_nop 2
	v_max_f32_e64 v251, |v80|, |v80|
	v_max_f32_e32 v80, v183, v183
	s_waitcnt lgkmcnt(0)
	v_max_f32_e64 v251, |v251|, |v251|
	v_max_f32_e32 v251, v251, v252
	v_max_f32_e64 v252, |v81|, |v81|
	v_rcp_f32_e32 v251, v251
	v_mfma_f32_16x16x32_bf16 v[116:119], v[190:193], v[198:201], v[116:119]
	global_load_dwordx4 v[52:55], v[246:247], off
	v_lshl_add_u64 v[246:247], v[246:247], 0, s[100:101]
	s_waitcnt lgkmcnt(0)
	v_max_f32_e64 v252, |v252|, |v252|
	v_max_f32_e32 v252, v252, v80
	v_rcp_f32_e32 v252, v252
	v_max_f32_e64 v80, |v82|, |v82|
	s_nop 2
	v_mul_f32_e32 v251, v116, v251
	v_cvt_pk_bf16_f32 v251, v251, s0
	ds_write_b16 v174, v251
	v_mul_f32_e32 v251, v117, v252
	v_cvt_pk_bf16_f32 v251, v251, s0
	ds_write_b16 v174, v251 offset:80
	s_waitcnt lgkmcnt(2)
	v_max_f32_e64 v251, |v80|, |v80|
	v_max_f32_e32 v252, v184, v184
	v_max_f32_e32 v251, v251, v252
	v_max_f32_e64 v252, |v83|, |v83|
	v_rcp_f32_e32 v251, v251
	v_mfma_f32_16x16x32_bf16 v[80:83], v[202:205], v[226:229], v[68:71]
	s_waitcnt lgkmcnt(0)
	v_max_f32_e64 v252, |v252|, |v252|
	s_nop 0
	v_max_f32_e32 v68, v185, v185
	v_max_f32_e32 v252, v252, v68
	v_rcp_f32_e32 v252, v252
	v_mfma_f32_16x16x32_bf16 v[76:79], v[202:205], v[214:217], v[76:79]
	s_mov_b64 s[94:95], exec
	s_mov_b64 exec, s[4:5]
	global_load_dwordx4 v[60:63], v[248:249], off
	s_mov_b64 exec, s[94:95]
	v_lshl_add_u64 v[248:249], v[248:249], 0, s[98:99]
	v_mul_f32_e32 v251, v118, v251
	v_cvt_pk_bf16_f32 v251, v251, s0
	ds_write_b16 v174, v251 offset:160
	v_mfma_f32_16x16x32_bf16 v[72:75], v[202:205], v[206:209], v[72:75]
	v_mul_f32_e32 v251, v119, v252
	v_cvt_pk_bf16_f32 v251, v251, s0
	ds_write_b16 v174, v251 offset:240
	v_mfma_f32_16x16x32_bf16 v[76:79], v[210:213], v[218:221], v[76:79]
	v_max_f32_e32 v251, v177, v177
	v_max_f32_e32 v252, v58, v58
	v_max_f32_e32 v251, v251, v252
	v_mfma_f32_16x16x32_bf16 v[68:71], v[210:213], v[222:225], v[72:75]
	ds_bpermute_b32 v181, v124, v251
	v_mfma_f32_16x16x32_bf16 v[72:75], v[210:213], v[230:233], v[80:83]
	s_nop 2
	v_cvt_pk_bf16_f32 v80, v76, v77
	v_cvt_pk_bf16_f32 v81, v78, v79
	ds_write_b64 v175, v[80:81] offset:34816
	v_cvt_pk_bf16_f32 v80, v68, v69
	v_cvt_pk_bf16_f32 v81, v70, v71
	ds_write_b64 v176, v[80:81] offset:34816
	v_cvt_pk_bf16_f32 v80, v72, v73
	v_cvt_pk_bf16_f32 v81, v74, v75
	ds_write_b64 v176, v[80:81] offset:39168
	s_and_saveexec_b64 s[92:93], s[6:7]
	s_cbranch_execz .LBB0_456
	ds_write_b32 v133, v57
	ds_write_b32 v132, v251

.LBB0_461:
	s_or_b64 exec, exec, s[92:93]
	v_sub_f32_e32 v251, v57, v181
	v_mul_f32_e32 v251, 0x3fb8aa3b, v251
	v_exp_f32_e32 v252, v251
	s_waitcnt vmcnt(7)
	ds_write_b128 v95, v[16:19] offset:47872
	ds_write_b128 v97, v[28:31] offset:47872
	s_and_saveexec_b64 s[92:93], s[4:5]
	s_cbranch_execz .LBB0_463
	ds_bpermute_b32 v251, v139, v252
	s_waitcnt lgkmcnt(3)
	v_cndmask_b32_e64 v80, v5, v4, s[16:17]
	v_cndmask_b32_e64 v81, v7, v6, s[16:17]
	v_cndmask_b32_e64 v82, v81, v80, s[18:19]
	v_lshlrev_b32_e32 v83, 16, v82
	s_waitcnt lgkmcnt(0)
	v_mul_f32_e32 v83, v83, v251
	v_cvt_pk_bf16_f32 v83, v83, s0
	ds_write_b16 v148, v82
	ds_write_b16 v149, v83
	ds_write_b16_d16_hi v150, v82
	v_and_b32_e32 v82, 0xffff0000, v82
	v_mul_f32_e32 v82, v82, v251
	v_cvt_pk_bf16_f32 v82, v82, s0
	ds_write_b16 v151, v82
	v_cndmask_b32_e64 v82, v4, v5, s[16:17]
	v_cndmask_b32_e64 v83, v6, v7, s[16:17]
	v_cndmask_b32_e64 v82, v83, v82, s[20:21]
	ds_write_b16 v152, v82
	v_lshlrev_b32_e32 v82, 16, v82
	v_mul_f32_e32 v82, v82, v251
	v_cvt_pk_bf16_f32 v82, v82, s0
	ds_write_b16 v153, v82
	v_cndmask_b32_e64 v82, v5, v4, s[22:23]
	v_cndmask_b32_e64 v83, v7, v6, s[22:23]
	v_cndmask_b32_e64 v82, v83, v82, s[24:25]
	ds_write_b16_d16_hi v154, v82
	v_and_b32_e32 v82, 0xffff0000, v82
	v_mul_f32_e32 v82, v82, v251
	v_cvt_pk_bf16_f32 v82, v82, s0
	v_cndmask_b32_e64 v80, v80, v81, s[18:19]
	ds_write_b16 v155, v82
	ds_write_b16 v156, v80
	v_lshlrev_b32_e32 v80, 16, v80
	v_mul_f32_e32 v80, v80, v251
	v_cvt_pk_bf16_f32 v80, v80, s0
	ds_write_b16 v157, v80
	v_cndmask_b32_e64 v80, v5, v4, s[26:27]
	v_cndmask_b32_e64 v81, v7, v6, s[26:27]
	v_cndmask_b32_e64 v80, v81, v80, s[28:29]
	ds_write_b16_d16_hi v158, v80
	v_and_b32_e32 v80, 0xffff0000, v80
	v_mul_f32_e32 v80, v80, v251
	v_cvt_pk_bf16_f32 v80, v80, s0
	ds_write_b16 v159, v80
	v_cndmask_b32_e64 v80, v5, v4, s[30:31]
	v_cndmask_b32_e64 v81, v7, v6, s[30:31]
	v_cndmask_b32_e64 v80, v81, v80, s[34:35]
	ds_write_b16 v160, v80
	v_lshlrev_b32_e32 v80, 16, v80
	v_mul_f32_e32 v80, v80, v251
	v_cvt_pk_bf16_f32 v80, v80, s0
	ds_write_b16 v161, v80
	v_cndmask_b32_e64 v80, v5, v4, s[36:37]
	v_cndmask_b32_e64 v81, v7, v6, s[36:37]
	v_cndmask_b32_e64 v80, v81, v80, s[38:39]
	ds_write_b16_d16_hi v162, v80
	v_and_b32_e32 v80, 0xffff0000, v80
	v_mul_f32_e32 v251, v80, v251
	v_cvt_pk_bf16_f32 v251, v251, s0
	ds_write_b16 v163, v251

.LBB0_465:
	s_or_b64 exec, exec, s[92:93]
.LBB0_469:
	v_sub_f32_e32 v251, v177, v181
	v_mul_f32_e32 v251, 0x3fb8aa3b, v251
	v_exp_f32_e32 v114, v251
	v_mov_b32_e32 v251, 0
	s_waitcnt lgkmcnt(2)
	v_mov_b32_e32 v80, 0
	v_mov_b32_e32 v81, 0
	v_mov_b32_e32 v82, 0
	v_mov_b32_e32 v83, 0
	s_and_saveexec_b64 s[92:93], s[12:13]
	s_cbranch_execz .LBB0_471
	ds_read_b128 v[80:83], v100 offset:17408
	ds_read_b128 v[184:187], v100 offset:17472
	ds_read_b128 v[188:191], v169
	ds_read_b128 v[192:195], v169 offset:64
	s_waitcnt lgkmcnt(1)
	v_mfma_f32_16x16x32_bf16 v[80:83], v[80:83], v[188:191], 0
	ds_read_b128 v[188:191], v100 offset:17536
	ds_read_b128 v[196:199], v100 offset:17600
	s_waitcnt lgkmcnt(2)
	v_mfma_f32_16x16x32_bf16 v[80:83], v[184:187], v[192:195], v[80:83]
	ds_read_b128 v[184:187], v169 offset:128
	ds_read_b128 v[192:195], v169 offset:192
	s_waitcnt lgkmcnt(1)
	v_mfma_f32_16x16x32_bf16 v[80:83], v[188:191], v[184:187], v[80:83]
	s_waitcnt lgkmcnt(0)
	v_mfma_f32_16x16x32_bf16 v[80:83], v[196:199], v[192:195], v[80:83]
.LBB0_471:
	s_or_b64 exec, exec, s[92:93]
	global_load_dwordx4 v[56:59], v[0:1], off
	v_add_co_u32_e32 v0, vcc, 0x400, v0
	s_nop 1
	v_addc_co_u32_e32 v1, vcc, 0, v1, vcc
	ds_read_b32 v111, v166
	s_and_saveexec_b64 s[92:93], s[40:41]
	s_cbranch_execz .LBB0_473
	ds_read_b32 v251, v142
	s_waitcnt lgkmcnt(0)
	v_sub_f32_e32 v251, v251, v111
	v_min_f32_e32 v251, 0, v251
	v_mul_f32_e32 v251, 0x3fb8aa3b, v251
	v_exp_f32_e32 v251, v251
	s_nop 0
	v_mul_f32_e32 v251, v80, v251
	v_cvt_pk_bf16_f32 v251, v251, s0

.LBB0_479:
	s_or_b64 exec, exec, s[92:93]
	global_load_dwordx4 v[8:11], v[240:241], off
	global_load_dwordx4 v[12:15], v[240:241], off offset:2048
	v_lshl_add_u64 v[240:241], v[240:241], 0, s[98:99]
	v_perm_b32 v82, v183, v251, s97
	v_perm_b32 v83, v81, v177, s97
	ds_write_b64 v170, v[82:83]
	v_mov_b32_e32 v81, 0
	v_mov_b32_e32 v82, 0
	v_mov_b32_e32 v83, 0
	s_and_saveexec_b64 s[92:93], s[14:15]
	s_cbranch_execz .LBB0_481
	ds_read_b128 v[80:83], v100 offset:17408
	ds_read_b128 v[184:187], v100 offset:17472
	ds_read_b128 v[188:191], v171
	ds_read_b128 v[192:195], v171 offset:64
	s_waitcnt lgkmcnt(1)
	v_mfma_f32_16x16x32_bf16 v[80:83], v[80:83], v[188:191], 0
	ds_read_b128 v[188:191], v100 offset:17536
	ds_read_b128 v[196:199], v100 offset:17600
	s_waitcnt lgkmcnt(2)
	v_mfma_f32_16x16x32_bf16 v[80:83], v[184:187], v[192:195], v[80:83]
	ds_read_b128 v[184:187], v171 offset:128
	ds_read_b128 v[192:195], v171 offset:192
	s_waitcnt lgkmcnt(1)
	v_mfma_f32_16x16x32_bf16 v[80:83], v[188:191], v[184:187], v[80:83]
	s_waitcnt lgkmcnt(0)
	v_mfma_f32_16x16x32_bf16 v[80:83], v[196:199], v[192:195], v[80:83]
.LBB0_481:
	s_or_b64 exec, exec, s[92:93]
	global_load_dwordx4 v[20:23], v[244:245], off
	global_load_dwordx4 v[24:27], v[244:245], off offset:2048
	v_lshl_add_u64 v[244:245], v[244:245], 0, s[98:99]
	ds_read_b32 v177, v167
	v_mov_b32_e32 v251, 0
	s_waitcnt lgkmcnt(2)
	v_mov_b32_e32 v111, 0
	s_and_saveexec_b64 s[92:93], s[48:49]
	s_cbranch_execz .LBB0_483
	ds_read_b32 v111, v142
	s_waitcnt lgkmcnt(0)
	v_sub_f32_e32 v111, v111, v177
	v_min_f32_e32 v111, 0, v111
	v_mul_f32_e32 v111, 0x3fb8aa3b, v111
	v_exp_f32_e32 v111, v111
	s_nop 0
	v_mul_f32_e32 v80, v80, v111
	v_cvt_pk_bf16_f32 v111, v80, s0

.LBB0_489:
	s_or_b64 exec, exec, s[92:93]
	v_perm_b32 v82, v251, v111, s97
	v_perm_b32 v83, v80, v81, s97
	ds_write_b64 v172, v[82:83]
	ds_read_b128 v[80:83], v100
	ds_read_b128 v[184:187], v101 offset:34816
	ds_read_b128 v[188:191], v100 offset:64
	ds_read_b128 v[192:195], v101 offset:34880
	ds_read_b128 v[196:199], v253 offset:43520
	ds_read_b128 v[200:203], v253 offset:43584
	s_waitcnt lgkmcnt(4)
	v_mfma_f32_16x16x32_bf16 v[184:187], v[80:83], v[184:187], 0
	v_add_f32_e32 v177, v181, v182
	v_pk_mul_f32 v[78:79], v[78:79], v[114:115] op_sel_hi:[1,0]
	v_pk_mul_f32 v[76:77], v[76:77], v[114:115] op_sel_hi:[1,0]
	s_waitcnt lgkmcnt(1)
	v_mfma_f32_16x16x32_bf16 v[80:83], v[80:83], v[196:199], 0
	v_mul_f32_e64 v70, v70, v114
	v_mul_f32_e64 v71, v71, v114
	v_pk_mul_f32 v[68:69], v[68:69], v[114:115] op_sel_hi:[1,0]
	v_pk_mul_f32 v[74:75], v[74:75], v[114:115] op_sel_hi:[1,0]
	v_mfma_f32_16x16x32_bf16 v[184:187], v[188:191], v[192:195], v[184:187]
	ds_read_b128 v[192:195], v100 offset:128
	ds_read_b128 v[196:199], v101 offset:34944
	v_pk_mul_f32 v[72:73], v[72:73], v[114:115] op_sel_hi:[1,0]
	s_add_i32 s72, s1, 1
	s_waitcnt lgkmcnt(2)
	v_mfma_f32_16x16x32_bf16 v[80:83], v[188:191], v[200:203], v[80:83]
	ds_read_b128 v[188:191], v253 offset:43648
	ds_read_b128 v[200:203], v100 offset:192
	ds_read_b128 v[204:207], v101 offset:35008
	s_cmpk_lt_u32 s72, 0x7f
	s_cselect_b64 s[92:93], -1, 0
	s_waitcnt lgkmcnt(3)
	v_mfma_f32_16x16x32_bf16 v[184:187], v[192:195], v[196:199], v[184:187]
	ds_read_b128 v[196:199], v253 offset:43712
	s_waitcnt lgkmcnt(0)
	s_barrier
	v_mfma_f32_16x16x32_bf16 v[80:83], v[192:195], v[188:191], v[80:83]
	ds_read_b128 v[188:191], v147
	ds_read_b128 v[192:195], v146
	s_cmpk_gt_u32 s72, 0x7e
	v_mfma_f32_16x16x32_bf16 v[80:83], v[200:203], v[196:199], v[80:83]
	ds_read_b128 v[196:199], v127
	v_mfma_f32_16x16x32_bf16 v[182:185], v[200:203], v[204:207], v[184:187]
	ds_read_b128 v[200:203], v254 offset:4608
	ds_read_b128 v[204:207], v127 offset:64
	ds_read_b128 v[208:211], v128
	ds_read_b128 v[212:215], v128 offset:64
	ds_read_b128 v[216:219], v254 offset:4672
	s_waitcnt lgkmcnt(6)
	v_pk_mul_f32 v[82:83], v[82:83], v[194:195]
	v_pk_mul_f32 v[80:81], v[80:81], v[192:193]
	v_pk_mul_f32 v[184:185], v[184:185], v[194:195]
	v_pk_mul_f32 v[182:183], v[182:183], v[192:193]
	s_waitcnt lgkmcnt(4)
	v_mfma_f32_16x16x32_bf16 v[80:83], v[196:199], v[200:203], v[80:83]
	ds_read_b128 v[192:195], v102 offset:47872
	ds_read_b128 v[200:203], v102 offset:47936
	ds_read_b128 v[220:223], v180
	ds_read_b128 v[224:227], v180 offset:64
	s_waitcnt lgkmcnt(4)
	v_mfma_f32_16x16x32_bf16 v[80:83], v[204:207], v[216:219], v[80:83]
	global_load_dwordx4 v[16:19], v[242:243], off
	v_lshl_add_u64 v[242:243], v[242:243], 0, s[100:101]
	ds_read_b128 v[216:219], v173
	ds_read_b128 v[228:231], v173 offset:64
	ds_read_b128 v[232:235], v173 offset:2304
	ds_read_b128 v[236:239], v173 offset:2368
	v_mfma_f32_16x16x32_bf16 v[180:183], v[196:199], v[208:211], v[182:185]
	s_nop 2
	v_max_f32_e64 v251, |v80|, |v80|
	v_max_f32_e32 v80, v188, v188
	v_max_f32_e64 v111, |v83|, |v83|
	v_mfma_f32_16x16x32_bf16 v[180:183], v[204:207], v[212:215], v[180:183]
	global_load_dwordx4 v[28:31], v[246:247], off
	v_lshl_add_u64 v[246:247], v[246:247], 0, s[100:101]
	s_waitcnt lgkmcnt(0)
	v_max_f32_e64 v251, |v251|, |v251|
	v_max_f32_e32 v251, v251, v80
	v_max_f32_e64 v80, |v81|, |v81|
	v_rcp_f32_e32 v251, v251
	v_max_f32_e32 v81, v189, v189
	v_mfma_f32_16x16x32_bf16 v[76:79], v[192:195], v[220:223], v[76:79]
	s_waitcnt lgkmcnt(0)
	v_max_f32_e64 v80, |v80|, |v80|
	v_max_f32_e32 v80, v80, v81
	v_rcp_f32_e32 v80, v80
	v_max_f32_e64 v81, |v82|, |v82|
	v_mul_f32_e32 v251, v180, v251
	v_cvt_pk_bf16_f32 v251, v251, s0
	ds_write_b16 v174, v251
	v_mul_f32_e32 v251, v181, v80
	v_cvt_pk_bf16_f32 v251, v251, s0
	ds_write_b16 v174, v251 offset:80
	s_waitcnt lgkmcnt(2)
	v_max_f32_e64 v251, |v81|, |v81|
	v_max_f32_e32 v80, v190, v190
	v_max_f32_e32 v251, v251, v80
	v_rcp_f32_e32 v251, v251
	v_mfma_f32_16x16x32_bf16 v[68:71], v[192:195], v[216:219], v[68:71]
	s_mov_b64 s[94:95], exec
	s_mov_b64 exec, s[4:5]
	global_load_dwordx4 v[4:7], v[248:249], off
	s_mov_b64 exec, s[94:95]
	v_lshl_add_u64 v[248:249], v[248:249], 0, s[98:99]
	v_mul_f32_e32 v251, v182, v251
	v_mfma_f32_16x16x32_bf16 v[80:83], v[192:195], v[232:235], v[72:75]
	v_cvt_pk_bf16_f32 v251, v251, s0
	ds_write_b16 v174, v251 offset:160
	s_nop 0
	v_max_f32_e64 v72, |v111|, |v111|
	v_max_f32_e32 v73, v191, v191
	v_max_f32_e32 v72, v72, v73
	v_rcp_f32_e32 v111, v72
	v_mfma_f32_16x16x32_bf16 v[76:79], v[200:203], v[224:227], v[76:79]
	v_mul_f32_e32 v251, v183, v111
	v_mfma_f32_16x16x32_bf16 v[72:75], v[200:203], v[228:231], v[68:71]
	v_cvt_pk_bf16_f32 v251, v251, s0
	ds_write_b16 v174, v251 offset:240
	v_mfma_f32_16x16x32_bf16 v[68:71], v[200:203], v[236:239], v[80:83]
	s_nop 2
	v_cvt_pk_bf16_f32 v80, v76, v77
	v_cvt_pk_bf16_f32 v81, v78, v79
	ds_write_b64 v175, v[80:81] offset:34816
	v_cvt_pk_bf16_f32 v80, v72, v73
	v_cvt_pk_bf16_f32 v81, v74, v75
	ds_write_b64 v176, v[80:81] offset:34816
	v_cvt_pk_bf16_f32 v80, v68, v69
	v_cvt_pk_bf16_f32 v81, v70, v71
	ds_write_b64 v176, v[80:81] offset:39168
	s_cbranch_scc1 .LBB0_493
	s_waitcnt vmcnt(9)
	v_max_f32_e32 v251, v177, v177
	v_max_f32_e32 v252, v66, v66
	v_max_f32_e32 v81, v251, v252
	ds_bpermute_b32 v251, v124, v81
	ds_bpermute_b32 v80, v124, v64
	s_and_saveexec_b64 s[94:95], s[6:7]
	s_cbranch_execz .LBB0_492
	ds_write_b32 v133, v65
	ds_write_b32 v132, v81

.LBB0_499:
	s_or_b64 exec, exec, s[92:93]
	s_waitcnt vmcnt(7)
	ds_write_b128 v95, v[40:43] offset:47872
	ds_write_b128 v97, v[52:55] offset:47872
	s_and_saveexec_b64 s[92:93], s[4:5]
	s_cbranch_execz .LBB0_501
	ds_bpermute_b32 v251, v139, v252
	s_waitcnt lgkmcnt(3)
	v_cndmask_b32_e64 v80, v61, v60, s[16:17]
	v_cndmask_b32_e64 v81, v63, v62, s[16:17]
	v_cndmask_b32_e64 v82, v81, v80, s[18:19]
	v_lshlrev_b32_e32 v83, 16, v82
	s_waitcnt lgkmcnt(0)
	v_mul_f32_e32 v83, v83, v251
	v_cvt_pk_bf16_f32 v83, v83, s0
	ds_write_b16 v148, v82
	ds_write_b16 v149, v83
	ds_write_b16_d16_hi v150, v82
	v_and_b32_e32 v82, 0xffff0000, v82
	v_mul_f32_e32 v82, v82, v251
	v_cvt_pk_bf16_f32 v82, v82, s0
	ds_write_b16 v151, v82
	v_cndmask_b32_e64 v82, v60, v61, s[16:17]
	v_cndmask_b32_e64 v83, v62, v63, s[16:17]
	v_cndmask_b32_e64 v82, v83, v82, s[20:21]
	ds_write_b16 v152, v82
	v_lshlrev_b32_e32 v82, 16, v82
	v_mul_f32_e32 v82, v82, v251
	v_cvt_pk_bf16_f32 v82, v82, s0
	ds_write_b16 v153, v82
	v_cndmask_b32_e64 v82, v61, v60, s[22:23]
	v_cndmask_b32_e64 v83, v63, v62, s[22:23]
	v_cndmask_b32_e64 v82, v83, v82, s[24:25]
	ds_write_b16_d16_hi v154, v82
	v_and_b32_e32 v82, 0xffff0000, v82
	v_mul_f32_e32 v82, v82, v251
	v_cvt_pk_bf16_f32 v82, v82, s0
	v_cndmask_b32_e64 v80, v80, v81, s[18:19]
	ds_write_b16 v155, v82
	ds_write_b16 v156, v80
	v_lshlrev_b32_e32 v80, 16, v80
	v_mul_f32_e32 v80, v80, v251
	v_cvt_pk_bf16_f32 v80, v80, s0
	ds_write_b16 v157, v80
	v_cndmask_b32_e64 v80, v61, v60, s[26:27]
	v_cndmask_b32_e64 v81, v63, v62, s[26:27]
	v_cndmask_b32_e64 v80, v81, v80, s[28:29]
	ds_write_b16_d16_hi v158, v80
	v_and_b32_e32 v80, 0xffff0000, v80
	v_mul_f32_e32 v80, v80, v251
	v_cvt_pk_bf16_f32 v80, v80, s0
	ds_write_b16 v159, v80
	v_cndmask_b32_e64 v80, v61, v60, s[30:31]
	v_cndmask_b32_e64 v81, v63, v62, s[30:31]
	v_cndmask_b32_e64 v80, v81, v80, s[34:35]
	ds_write_b16 v160, v80
	v_lshlrev_b32_e32 v80, 16, v80
	v_mul_f32_e32 v80, v80, v251
	v_cvt_pk_bf16_f32 v80, v80, s0
	ds_write_b16 v161, v80
	v_cndmask_b32_e64 v80, v61, v60, s[36:37]
	v_cndmask_b32_e64 v81, v63, v62, s[36:37]
	v_cndmask_b32_e64 v80, v81, v80, s[38:39]
	ds_write_b16_d16_hi v162, v80
	v_and_b32_e32 v80, 0xffff0000, v80
	v_mul_f32_e32 v251, v80, v251
	v_cvt_pk_bf16_f32 v251, v251, s0
	ds_write_b16 v163, v251

.LBB0_504:
	s_branch .LBB0_435

.LBB0_509:
	s_waitcnt vmcnt(0)
	v_mov_b32_e32 v0, v85
	v_mov_b32_e32 v1, v85
	v_mov_b32_e32 v2, v85
	v_mov_b32_e32 v3, v85
	s_mov_b64 s[0:1], 0
	s_movk_i32 s25, 0x110

.LBB0_522:
	s_or_b64 exec, exec, s[0:1]
	v_ashrrev_i32_e32 v92, 7, v68
	v_and_b32_e32 v81, 15, v68
	v_lshlrev_b32_e32 v94, 4, v92
	v_or_b32_e32 v95, v94, v81
	s_and_b32 s12, s2, 1
	v_mul_lo_u32 v96, v95, s25
	v_and_b32_e32 v98, 48, v79
	v_mul_lo_u32 v95, v95, s33
	v_readlane_b32 s2, v250, 56
	v_ashrrev_i32_e32 v90, 6, v68
	s_lshl_b32 s0, s59, 2
	v_add3_u32 v128, s2, v95, v98
	s_mov_b32 s2, s61
	v_add3_u32 v131, s2, v83, v80
	v_and_b32_e32 v83, 64, v123
	v_xor_b32_e32 v80, 1, v123
	v_add_u32_e32 v83, 64, v83
	s_add_i32 s10, 0, 0x1c800
	v_cmp_lt_i32_e32 vcc, v80, v83
	s_and_b32 s0, s0, -16
	v_lshlrev_b32_e32 v93, 1, v90
	v_lshl_add_u32 v106, v92, 6, s10
	v_cndmask_b32_e32 v80, v123, v80, vcc
	v_lshl_add_u32 v135, v79, 2, s10
	s_lshl_b32 s10, s18, 2
	v_lshrrev_b32_e32 v91, 4, v79
	v_and_b32_e32 v93, 2, v93
	v_lshlrev_b32_e32 v132, 2, v80
	v_xor_b32_e32 v80, 2, v123
	s_add_i32 s14, s0, s10
	s_bfe_u32 s1, s57, 0x10004
	v_lshlrev_b32_e32 v97, 3, v91
	v_add3_u32 v121, 0, v96, v98
	v_lshl_or_b32 v96, v93, 4, v81
	v_lshlrev_b32_e32 v92, 5, v92
	v_readlane_b32 s3, v250, 57
	v_readlane_b32 s6, v250, 58
	v_cmp_lt_i32_e32 vcc, v80, v83
	s_lshr_b32 s0, s14, 1
	v_lshl_or_b32 v91, v91, 2, v94
	v_add3_u32 v94, s3, v92, v97
	v_add3_u32 v92, s6, v92, v97
	v_add_u32_e32 v108, s6, v98
	v_cndmask_b32_e32 v80, v123, v80, vcc
	v_cmp_eq_u32_e64 s[6:7], 0, v82
	v_mul_u32_u24_e32 v82, 0x48, v96
	s_or_b32 s0, s0, s1
	v_lshlrev_b32_e32 v133, 2, v80
	v_xor_b32_e32 v80, 4, v123
	v_lshlrev_b32_e32 v82, 1, v82
	s_and_b32 s15, s0, 31
	v_mul_u32_u24_e32 v95, 0x90, v96
	v_cmp_lt_i32_e32 vcc, v80, v83
	v_add_u32_e32 v136, v94, v82
	v_add_u32_e32 v137, v92, v82
	v_or_b32_e32 v82, 1, v93
	s_add_i32 s0, s19, s15
	v_add3_u32 v129, s3, v95, v98
	v_cndmask_b32_e32 v80, v123, v80, vcc
	s_mov_b32 s3, s60
	v_lshl_or_b32 v83, v82, 4, v81
	s_ashr_i32 s1, s0, 31
	s_lshl_b32 s13, s12, 7
	v_lshl_or_b32 v95, v90, 4, v81
	v_lshlrev_b32_e32 v134, 2, v80
	v_lshl_add_u32 v80, v96, 1, s3
	v_lshl_add_u32 v110, v83, 1, s3
	s_lshl_b64 s[10:11], s[0:1], 15
	s_lshl_b64 s[0:1], s[0:1], 20
	v_readlane_b32 s3, v250, 51
	v_mul_lo_u32 v95, v95, s33
	v_mul_u32_u24_e32 v83, 0x48, v83
	s_add_u32 s0, s3, s0
	v_readlane_b32 s3, v250, 52
	v_add3_u32 v130, 0, v95, v98
	v_lshl_add_u32 v95, v81, 1, s2
	v_lshlrev_b32_e32 v90, 5, v90
	v_lshlrev_b32_e32 v83, 1, v83
	s_addc_u32 s1, s3, s1
	v_and_b32_e32 v107, 48, v68
	v_add3_u32 v109, 0, v90, v97
	v_mul_lo_u32 v79, v91, s33
	v_add_u32_e32 v139, v92, v83
	v_lshl_add_u32 v111, v93, 5, v95
	v_lshl_add_u64 v[90:91], v[68:69], 2, s[10:11]
	v_lshl_add_u64 v[92:93], v[72:73], 1, s[0:1]
	v_mad_i64_i32 v[68:69], s[0:1], v76, s96, 0
	v_add_u32_e32 v138, v94, v83
	v_lshl_add_u32 v82, v82, 5, v95
	v_mad_i64_i32 v[94:95], s[0:1], s8, v126, v[68:69]
	s_lshl_b32 s16, s15, 8
	v_or_b32_e32 v68, s16, v94
	v_or3_b32 v94, v68, s13, v78
	v_mad_i64_i32 v[68:69], s[0:1], v74, s96, 0
	v_mul_u32_u24_e32 v99, 0x110, v96
	v_mad_i64_i32 v[96:97], s[0:1], s8, v126, v[68:69]
	s_lshl_b32 s0, s14, 6
	s_and_b32 s13, s0, 0xf00
	s_lshl_b64 s[0:1], s[8:9], 26
	v_lshlrev_b64 v[68:69], 13, v[74:75]
	v_add3_u32 v127, 0, v99, v98
	v_lshl_add_u64 v[98:99], s[0:1], 0, v[68:69]
	v_mad_i64_i32 v[68:69], s[10:11], v70, s96, 0
	v_mad_i64_i32 v[100:101], s[10:11], s8, v126, v[68:69]
	v_lshlrev_b64 v[68:69], 13, v[70:71]
	v_lshl_add_u64 v[102:103], s[0:1], 0, v[68:69]
	s_lshl_b32 s0, s8, 6
	s_lshl_b32 s1, s15, 1
	s_or_b32 s0, s0, s1
	s_or_b32 s0, s0, s12
	s_ashr_i32 s1, s0, 31
	v_mul_u32_u24_e32 v83, 0x90, v81
	v_mul_u32_u24_e32 v112, 0x110, v81
	v_lshlrev_b32_e32 v72, 4, v81
	s_lshl_b64 s[0:1], s[0:1], 15
	v_mov_b32_e32 v68, 0
	s_mov_b32 s2, 0
	v_or3_b32 v96, v96, s13, v72
	v_or3_b32 v98, v98, s16, v72
	v_or3_b32 v100, v100, s13, v72
	v_or3_b32 v102, v102, s16, v72
	v_lshl_add_u64 v[104:105], v[76:77], 2, s[0:1]
	v_add_u32_e32 v140, v106, v107
	v_add_u32_e32 v141, v80, v79
	v_add_u32_e32 v142, v110, v79
	v_add_u32_e32 v143, v108, v83
	v_add_u32_e32 v144, v111, v79
	v_add_u32_e32 v145, v82, v79
	v_add_u32_e32 v146, v109, v112
	v_mov_b32_e32 v69, v68
	v_mov_b32_e32 v70, v68
	v_mov_b32_e32 v71, v68
	v_mov_b32_e32 v72, v68
	v_mov_b32_e32 v73, v68
	v_mov_b32_e32 v74, v68
	v_mov_b32_e32 v75, v68
	v_mov_b32_e32 v76, v68
	v_mov_b32_e32 v77, v68
	v_mov_b32_e32 v78, v68
	v_mov_b32_e32 v79, v68
	v_mov_b32_e32 v80, v68
	v_mov_b32_e32 v81, v68
	v_mov_b32_e32 v82, v68
	v_mov_b32_e32 v83, v68
	s_waitcnt lgkmcnt(0)
	s_barrier
	s_mov_b32 s13, 0
	s_mov_b32 s15, 0
	s_mov_b32 s17, 0
	s_mov_b32 s19, 0
	s_mov_b32 s21, 0
	s_mov_b32 s23, 0
	s_mov_b32 s27, 0
	s_mov_b32 s29, 0
	v_lshl_add_u64 v[218:219], s[82:83], 0, v[102:103]
	v_lshl_add_u64 v[220:221], s[82:83], 0, v[100:101]
	v_lshl_add_u64 v[224:225], s[82:83], 0, v[98:99]
	v_lshl_add_u64 v[226:227], s[82:83], 0, v[96:97]
	v_lshl_add_u64 v[232:233], s[82:83], 0, v[94:95]
	v_lshl_add_u64 v[234:235], s[82:83], 0, v[90:91]
	v_mov_b32_e32 v230, v92
	v_mov_b32_e32 v231, v93
	v_add_co_u32_e32 v218, vcc, 0x21600000, v218
	s_nop 1
	v_addc_co_u32_e32 v219, vcc, 0, v219, vcc
	v_add_co_u32_e32 v224, vcc, 0x21600000, v224
	s_nop 1
	v_addc_co_u32_e32 v225, vcc, 0, v225, vcc
	v_add_co_u32_e32 v220, vcc, 0x8400000, v220
	s_nop 1
	v_addc_co_u32_e32 v221, vcc, 0, v221, vcc
	v_add_co_u32_e32 v226, vcc, 0x8400000, v226
	s_nop 1
	v_addc_co_u32_e32 v227, vcc, 0, v227, vcc
	v_add_co_u32_e32 v232, vcc, 0x8402000, v232
	s_nop 1
	v_addc_co_u32_e32 v233, vcc, 0, v233, vcc
	v_add_co_u32_e32 v234, vcc, 0x29500200, v234
	s_nop 1
	v_addc_co_u32_e32 v235, vcc, 0, v235, vcc
	v_add_co_u32_e32 v230, vcc, 0xffffe000, v230
	s_nop 1
	v_addc_co_u32_e32 v231, vcc, -1, v231, vcc
	v_add_co_u32_e32 v222, vcc, 0x1000, v220
	s_nop 1
	v_addc_co_u32_e32 v223, vcc, 0, v221, vcc
	v_add_co_u32_e32 v228, vcc, 0x1000, v226
	s_nop 1
	v_addc_co_u32_e32 v229, vcc, 0, v227, vcc
	s_branch .LBB0_525

.LBB0_525:
	s_cmpk_lt_u32 s2, 0x7d
	s_cselect_b32 s12, 0x180000, 0
	s_cselect_b32 s14, 0x80000, 0
	s_cselect_b32 s16, 0x2000, 0
	s_cselect_b32 s18, 0x100, 0
	s_cmpk_lt_u32 s2, 0x7b
	s_cselect_b32 s20, 0x180000, 0
	s_cselect_b32 s22, 0x80000, 0
	s_cselect_b32 s26, 0x2000, 0
	s_cselect_b32 s28, 0x100, 0
	ds_read_b128 v[106:109], v121
	ds_read_b128 v[110:113], v127 offset:34816
	ds_read_b128 v[114:117], v121 offset:64
	s_waitcnt lgkmcnt(3)
	ds_read_b128 v[148:151], v127 offset:34880
	ds_read_b128 v[156:159], v127 offset:39168
	ds_read_b128 v[160:163], v127 offset:39232
	ds_read_b128 v[166:169], v121 offset:128
	ds_read_b128 v[170:173], v127 offset:34944
	s_waitcnt lgkmcnt(6)
	v_mfma_f32_16x16x32_bf16 v[152:155], v[106:109], v[110:113], 0
	v_mov_b32_e32 v147, s56
	s_waitcnt lgkmcnt(3)
	v_mfma_f32_16x16x32_bf16 v[106:109], v[106:109], v[156:159], 0
	v_mfma_f32_16x16x32_bf16 v[152:155], v[114:117], v[148:151], v[152:155]
	s_waitcnt lgkmcnt(2)
	v_mfma_f32_16x16x32_bf16 v[106:109], v[114:117], v[160:163], v[106:109]
	global_load_dwordx4 v[36:39], v[218:219], off
	v_lshl_add_u64 v[218:219], v[218:219], 0, s[14:15]
	ds_read_b128 v[114:117], v127 offset:39296
	ds_read_b128 v[174:177], v121 offset:192
	ds_read_b128 v[178:181], v127 offset:35008
	ds_read_b128 v[182:185], v121 offset:17408
	ds_read_b128 v[186:189], v121 offset:17472
	ds_read_b128 v[190:193], v127 offset:39360
	s_waitcnt lgkmcnt(6)
	v_mfma_f32_16x16x32_bf16 v[152:155], v[166:169], v[170:173], v[152:155]
	s_waitcnt lgkmcnt(5)
	v_mfma_f32_16x16x32_bf16 v[106:109], v[166:169], v[114:117], v[106:109]
	global_load_dwordx4 v[40:43], v[220:221], off
	v_lshl_add_u64 v[220:221], v[220:221], 0, s[12:13]
	ds_read_b32 v147, v147
	ds_read_b128 v[166:169], v140
	ds_read_b128 v[194:197], v121 offset:17536
	ds_read_b128 v[198:201], v121 offset:17600
	ds_read_u16 v204, v141
	ds_read_u16 v205, v141 offset:144
	s_waitcnt lgkmcnt(4)
	v_sub_f32_e32 v202, v147, v166
	v_mfma_f32_16x16x32_bf16 v[110:113], v[182:185], v[110:113], 0
	v_mul_f32_e32 v202, 0x3fb8aa3b, v202
	v_mul_f32_e32 v166, 0x3fb8aa3b, v166
	v_mfma_f32_16x16x32_bf16 v[156:159], v[182:185], v[156:159], 0
	v_mfma_f32_16x16x32_bf16 v[152:155], v[174:177], v[178:181], v[152:155]
	v_mfma_f32_16x16x32_bf16 v[106:109], v[174:177], v[190:193], v[106:109]
	global_load_dwordx4 v[48:51], v[224:225], off
	v_lshl_add_u64 v[224:225], v[224:225], 0, s[14:15]
	v_exp_f32_e32 v174, v202
	v_exp_f32_e32 v202, v166
	v_sub_f32_e32 v166, v147, v167
	v_mul_f32_e32 v167, 0x3fb8aa3b, v167
	v_exp_f32_e32 v203, v167
	v_sub_f32_e32 v167, v147, v168
	v_mfma_f32_16x16x32_bf16 v[110:113], v[186:189], v[148:151], v[110:113]
	v_mul_f32_e32 v148, 0x3fb8aa3b, v167
	v_exp_f32_e32 v167, v148
	v_mul_f32_e32 v166, 0x3fb8aa3b, v166
	v_mfma_f32_16x16x32_bf16 v[148:151], v[186:189], v[160:163], v[156:159]
	global_load_dwordx4 v[52:55], v[226:227], off
	v_lshl_add_u64 v[226:227], v[226:227], 0, s[12:13]
	v_exp_f32_e32 v166, v166
	v_mul_f32_e32 v168, 0x3fb8aa3b, v168
	v_exp_f32_e32 v182, v168
	s_waitcnt lgkmcnt(3)
	v_mfma_f32_16x16x32_bf16 v[114:117], v[194:197], v[114:117], v[148:151]
	s_nop 2
	ds_read_u16 v150, v141 offset:288
	ds_read_u16 v151, v141 offset:432
	v_sub_f32_e32 v156, v147, v169
	v_mul_f32_e32 v156, 0x3fb8aa3b, v156
	v_exp_f32_e32 v158, v156
	s_waitcnt lgkmcnt(2)
	v_lshlrev_b32_e32 v157, 16, v205
	v_lshlrev_b32_e32 v156, 16, v204
	s_waitcnt lgkmcnt(0)
	v_lshlrev_b32_e32 v151, 16, v151
	v_lshlrev_b32_e32 v150, 16, v150
	v_pk_add_f32 v[148:149], v[156:157], v[152:153] neg_lo:[0,1] neg_hi:[0,1]
	v_pk_add_f32 v[150:151], v[150:151], v[154:155] neg_lo:[0,1] neg_hi:[0,1]
	v_mul_f32_e32 v152, v174, v148
	v_mul_f32_e32 v153, v166, v149
	v_cvt_pk_bf16_f32 v148, v148, v149
	v_mul_f32_e32 v154, v167, v150
	v_mul_f32_e32 v155, v158, v151
	v_cvt_pk_bf16_f32 v149, v150, v151
	ds_write_b64 v136, v[148:149]
	v_cvt_pk_bf16_f32 v148, v152, v153
	v_cvt_pk_bf16_f32 v149, v154, v155
	ds_write_b64 v137, v[148:149]
	ds_read_u16 v148, v142
	ds_read_u16 v149, v142 offset:144
	v_mul_f32_e32 v150, 0x3fb8aa3b, v169
	v_mfma_f32_16x16x32_bf16 v[110:113], v[194:197], v[170:173], v[110:113]
	global_load_dwordx4 v[64:67], v[232:233], off
	v_lshl_add_u64 v[232:233], v[232:233], 0, s[12:13]
	v_exp_f32_e32 v183, v150
	ds_read_u16 v150, v142 offset:288
	ds_read_u16 v151, v142 offset:432
	s_waitcnt lgkmcnt(2)
	v_lshlrev_b32_e32 v149, 16, v149
	v_mfma_f32_16x16x32_bf16 v[110:113], v[198:201], v[178:181], v[110:113]
	s_mov_b64 s[30:31], exec
	s_mov_b64 exec, s[4:5]
	global_load_dword v84, v[234:235], off
	s_mov_b64 exec, s[30:31]
	v_lshl_add_u64 v[234:235], v[234:235], 0, s[18:19]
	v_lshlrev_b32_e32 v148, 16, v148
	v_pk_add_f32 v[106:107], v[148:149], v[106:107] neg_lo:[0,1] neg_hi:[0,1]
	s_waitcnt lgkmcnt(0)
	v_lshlrev_b32_e32 v149, 16, v151
	v_lshlrev_b32_e32 v148, 16, v150
	v_mfma_f32_16x16x32_bf16 v[114:117], v[198:201], v[190:193], v[114:117]
	v_add_f32_e64 v108, v148, -v108
	v_add_f32_e64 v109, v149, -v109
	v_mul_f32_e32 v152, v174, v106
	v_mul_f32_e32 v153, v166, v107
	v_cvt_pk_bf16_f32 v106, v106, v107
	v_mul_f32_e32 v148, v167, v108
	v_mul_f32_e32 v149, v158, v109
	v_cvt_pk_bf16_f32 v107, v108, v109
	ds_write_b64 v138, v[106:107]
	v_cvt_pk_bf16_f32 v106, v152, v153
	v_cvt_pk_bf16_f32 v107, v148, v149
	v_pk_mul_f32 v[110:111], v[110:111], v[202:203]
	v_pk_mul_f32 v[112:113], v[112:113], v[182:183]
	ds_write_b64 v139, v[106:107]
	s_waitcnt lgkmcnt(0)
	s_barrier
	ds_read_b128 v[106:109], v128
	ds_read_b128 v[148:151], v128 offset:64
	ds_read_b128 v[152:155], v129
	ds_read_b128 v[156:159], v129 offset:64
	ds_read_b128 v[160:163], v129 offset:2304
	ds_read_b128 v[166:169], v129 offset:2368
	ds_read_b128 v[170:173], v130 offset:52224
	ds_read_b128 v[174:177], v130 offset:52288
	s_waitcnt lgkmcnt(5)
	v_mfma_f32_16x16x32_bf16 v[110:113], v[106:109], v[152:155], v[110:113]
	v_mul_f32_e64 v114, v114, v202
	v_mul_f32_e64 v115, v115, v203
	v_pk_mul_f32 v[116:117], v[116:117], v[182:183]
	v_mul_f32_e32 v147, 0x3fb8aa3b, v147
	v_exp_f32_e32 v194, v147
	s_waitcnt lgkmcnt(3)
	v_mfma_f32_16x16x32_bf16 v[106:109], v[106:109], v[160:163], v[114:117]
	ds_read_b128 v[152:155], v143
	ds_read_b128 v[178:181], v143 offset:64
	s_nop 0
	ds_read_b128 v[114:117], v143 offset:2304
	ds_read_b128 v[160:163], v143 offset:2368
	ds_read_b128 v[182:185], v143 offset:4608
	ds_read_b128 v[186:189], v143 offset:4672
	v_pk_mul_f32 v[82:83], v[82:83], v[194:195] op_sel_hi:[1,0]
	v_mfma_f32_16x16x32_bf16 v[110:113], v[148:151], v[156:159], v[110:113]
	global_load_dwordx4 v[44:47], v[222:223], off
	v_lshl_add_u64 v[222:223], v[222:223], 0, s[12:13]
	ds_read_b128 v[156:159], v143 offset:6912
	ds_read_b128 v[190:193], v143 offset:6976
	v_pk_mul_f32 v[80:81], v[80:81], v[194:195] op_sel_hi:[1,0]
	v_pk_mul_f32 v[78:79], v[78:79], v[194:195] op_sel_hi:[1,0]
	s_waitcnt lgkmcnt(10)
	v_mfma_f32_16x16x32_bf16 v[106:109], v[148:151], v[166:169], v[106:109]
	v_mul_f32_e64 v76, v76, v194
	v_mul_f32_e64 v77, v77, v194
	v_pk_mul_f32 v[70:71], v[70:71], v[194:195] op_sel_hi:[1,0]
	v_pk_mul_f32 v[68:69], v[68:69], v[194:195] op_sel_hi:[1,0]
	s_waitcnt lgkmcnt(7)
	v_mfma_f32_16x16x32_bf16 v[80:83], v[170:173], v[152:155], v[80:83]
	v_mul_f32_e64 v74, v74, v194
	v_mul_f32_e64 v75, v75, v194
	v_pk_mul_f32 v[72:73], v[72:73], v[194:195] op_sel_hi:[1,0]
	v_cvt_pk_bf16_f32 v110, v110, s0
	s_waitcnt lgkmcnt(5)
	v_mfma_f32_16x16x32_bf16 v[76:79], v[170:173], v[114:117], v[76:79]
	global_load_dwordx4 v[56:59], v[228:229], off
	v_lshl_add_u64 v[228:229], v[228:229], 0, s[12:13]
	ds_write_b16 v144, v110
	v_cvt_pk_bf16_f32 v110, v111, s0
	ds_write_b16 v144, v110 offset:144
	s_waitcnt lgkmcnt(3)
	v_mfma_f32_16x16x32_bf16 v[114:117], v[170:173], v[156:159], v[68:71]
	s_nop 2
	v_cvt_pk_bf16_f32 v68, v112, s0
	v_mfma_f32_16x16x32_bf16 v[72:75], v[170:173], v[182:185], v[72:75]
	ds_write_b16 v144, v68 offset:288
	v_cvt_pk_bf16_f32 v68, v113, s0
	ds_write_b16 v144, v68 offset:432
	v_cvt_pk_bf16_f32 v68, v106, s0
	v_mfma_f32_16x16x32_bf16 v[80:83], v[174:177], v[178:181], v[80:83]
	ds_write_b16 v145, v68
	v_mfma_f32_16x16x32_bf16 v[68:71], v[174:177], v[160:163], v[76:79]
	global_load_dwordx4 v[60:63], v[230:231], off
	v_lshl_add_u64 v[230:231], v[230:231], 0, s[16:17]
	s_nop 2
	v_cvt_pk_bf16_f32 v76, v107, s0
	ds_write_b16 v145, v76 offset:144
	v_cvt_pk_bf16_f32 v76, v108, s0
	v_mfma_f32_16x16x32_bf16 v[72:75], v[174:177], v[186:189], v[72:75]
	ds_write_b16 v145, v76 offset:288
	v_cvt_pk_bf16_f32 v76, v109, s0
	ds_write_b16 v145, v76 offset:432
	s_waitcnt lgkmcnt(8)
	v_mfma_f32_16x16x32_bf16 v[76:79], v[174:177], v[190:193], v[114:117]
	v_cvt_pk_bf16_f32 v106, v80, v81
	v_cvt_pk_bf16_f32 v107, v82, v83
	ds_write_b64 v146, v[106:107] offset:34816
	v_cvt_pk_bf16_f32 v106, v68, v69
	v_cvt_pk_bf16_f32 v107, v70, v71
	ds_write_b64 v146, v[106:107] offset:39168
	v_cvt_pk_bf16_f32 v106, v72, v73
	v_cvt_pk_bf16_f32 v107, v74, v75
	ds_write_b64 v146, v[106:107] offset:43520
	v_cvt_pk_bf16_f32 v106, v76, v77
	v_cvt_pk_bf16_f32 v107, v78, v79
	ds_write_b64 v146, v[106:107] offset:47872
	s_waitcnt vmcnt(13)
	ds_write_b128 v86, v[4:7]
	ds_write_b128 v86, v[8:11] offset:17408
	ds_write_b128 v88, v[16:19]
	ds_write_b128 v88, v[20:23] offset:17408
	ds_write_b128 v87, v[32:35]
	s_and_saveexec_b64 s[0:1], s[4:5]
	ds_write_b32 v135, v118
	s_or_b64 exec, exec, s[0:1]
	s_waitcnt lgkmcnt(0)
	s_barrier
	ds_read_b128 v[110:113], v131
	s_waitcnt lgkmcnt(0)
	v_and_b32_e32 v107, 0xffff0000, v110
	v_lshlrev_b32_e32 v106, 16, v110
	v_mul_f32_e32 v107, v107, v107
	v_lshlrev_b32_e32 v108, 16, v111
	v_fmac_f32_e32 v107, v106, v106
	v_and_b32_e32 v109, 0xffff0000, v111
	v_fmac_f32_e32 v107, v108, v108
	v_lshlrev_b32_e32 v114, 16, v112
	v_fmac_f32_e32 v107, v109, v109
	v_and_b32_e32 v115, 0xffff0000, v112
	v_fmac_f32_e32 v107, v114, v114
	v_lshlrev_b32_e32 v116, 16, v113
	v_fmac_f32_e32 v107, v115, v115
	v_and_b32_e32 v117, 0xffff0000, v113
	v_fmac_f32_e32 v107, v116, v116
	v_fmac_f32_e32 v107, v117, v117
	s_nop 1
	v_add_f32_dpp v108, v107, v107 quad_perm:[1,0,3,2] row_mask:0xf bank_mask:0xf
	v_lshl_add_u64 v[106:107], s[82:83], 0, v[94:95]
	v_add_co_u32_e32 v114, vcc, 0x8102000, v106
	v_add_f32_dpp v109, v108, v108 quad_perm:[2,3,0,1] row_mask:0xf bank_mask:0xf
	s_nop 0
	v_addc_co_u32_e32 v115, vcc, 0, v107, vcc
	s_nop 0
	v_add_f32_dpp v108, v109, v109 row_half_mirror row_mask:0xf bank_mask:0xf
	global_store_dwordx4 v[114:115], v[110:113], off
	v_lshl_add_u64 v[114:115], s[82:83], 0, v[104:105]
	s_and_saveexec_b64 s[0:1], s[6:7]
	s_cbranch_execz .LBB0_529
	v_mov_b32_e32 v110, v108
	v_add_co_u32_e32 v108, vcc, 0x29760000, v114
	s_nop 1
	v_addc_co_u32_e32 v109, vcc, 0, v115, vcc
	global_store_dword v[108:109], v110, off
.LBB0_529:
	s_or_b64 exec, exec, s[0:1]
	s_waitcnt vmcnt(12)
	ds_write_b128 v89, v[12:15] offset:52224
	ds_write_b128 v119, v[24:27] offset:52224
	ds_write_b128 v120, v[28:31]
.LBB0_533:
	ds_read_b128 v[148:151], v121
	ds_read_b128 v[152:155], v127 offset:34816
	ds_read_b128 v[156:159], v121 offset:64
	ds_read_b128 v[160:163], v127 offset:34880
	ds_read_b128 v[170:173], v127 offset:39168
	ds_read_b128 v[174:177], v127 offset:39232
	ds_read_b128 v[178:181], v121 offset:128
	ds_read_b128 v[182:185], v127 offset:34944
	s_waitcnt lgkmcnt(6)
	v_mfma_f32_16x16x32_bf16 v[166:169], v[148:151], v[152:155], 0
	v_mov_b32_e32 v147, s56
	s_add_i32 s10, s2, 1
	s_cmpk_lt_u32 s10, 0x7f
	s_waitcnt lgkmcnt(3)
	v_mfma_f32_16x16x32_bf16 v[148:151], v[148:151], v[170:173], 0
	v_mfma_f32_16x16x32_bf16 v[166:169], v[156:159], v[160:163], v[166:169]
	s_waitcnt lgkmcnt(2)
	v_mfma_f32_16x16x32_bf16 v[148:151], v[156:159], v[174:177], v[148:151]
	global_load_dwordx4 v[4:7], v[218:219], off
	v_lshl_add_u64 v[218:219], v[218:219], 0, s[22:23]
	ds_read_b128 v[156:159], v127 offset:39296
	ds_read_b128 v[186:189], v121 offset:192
	ds_read_b128 v[190:193], v127 offset:35008
	ds_read_b128 v[194:197], v121 offset:17408
	ds_read_b128 v[198:201], v121 offset:17472
	ds_read_b128 v[202:205], v127 offset:39360
	s_waitcnt lgkmcnt(6)
	v_mfma_f32_16x16x32_bf16 v[166:169], v[178:181], v[182:185], v[166:169]
	s_waitcnt lgkmcnt(5)
	v_mfma_f32_16x16x32_bf16 v[148:151], v[178:181], v[156:159], v[148:151]
	global_load_dwordx4 v[8:11], v[220:221], off
	v_lshl_add_u64 v[220:221], v[220:221], 0, s[20:21]
	ds_read_b128 v[178:181], v121 offset:17536
	ds_read_b128 v[206:209], v121 offset:17600
	ds_read_b32 v147, v147
	ds_read_b128 v[210:213], v140
	ds_read_u16 v214, v141
	ds_read_u16 v215, v141 offset:144
	ds_read_u16 v216, v141 offset:288
	ds_read_u16 v217, v141 offset:432
	s_waitcnt lgkmcnt(10)
	v_mfma_f32_16x16x32_bf16 v[152:155], v[194:197], v[152:155], 0
	v_mfma_f32_16x16x32_bf16 v[170:173], v[194:197], v[170:173], 0
	v_mfma_f32_16x16x32_bf16 v[166:169], v[186:189], v[190:193], v[166:169]
	s_waitcnt lgkmcnt(8)
	v_mfma_f32_16x16x32_bf16 v[148:151], v[186:189], v[202:205], v[148:151]
	global_load_dwordx4 v[16:19], v[224:225], off
	v_lshl_add_u64 v[224:225], v[224:225], 0, s[22:23]
	s_waitcnt lgkmcnt(4)
	v_mul_f32_e32 v187, 0x3fb8aa3b, v210
	v_mul_f32_e32 v188, 0x3fb8aa3b, v211
	v_sub_f32_e32 v186, v147, v210
	v_mfma_f32_16x16x32_bf16 v[152:155], v[198:201], v[160:163], v[152:155]
	v_sub_f32_e32 v160, v147, v212
	v_exp_f32_e32 v210, v187
	v_sub_f32_e32 v187, v147, v211
	v_exp_f32_e32 v211, v188
	v_mul_f32_e32 v188, 0x3fb8aa3b, v160
	v_mfma_f32_16x16x32_bf16 v[160:163], v[198:201], v[174:177], v[170:173]
	global_load_dwordx4 v[20:23], v[226:227], off
	v_lshl_add_u64 v[226:227], v[226:227], 0, s[20:21]
	v_mul_f32_e32 v186, 0x3fb8aa3b, v186
	v_mul_f32_e32 v187, 0x3fb8aa3b, v187
	v_exp_f32_e32 v186, v186
	v_mul_f32_e32 v171, 0x3fb8aa3b, v212
	v_exp_f32_e32 v194, v171
	v_sub_f32_e32 v171, v147, v213
	v_mul_f32_e32 v171, 0x3fb8aa3b, v171
	v_exp_f32_e32 v187, v187
	v_exp_f32_e32 v170, v188
	v_exp_f32_e32 v171, v171
	v_mfma_f32_16x16x32_bf16 v[156:159], v[178:181], v[156:159], v[160:163]
	v_mul_f32_e32 v147, 0x3fb8aa3b, v147
	s_waitcnt lgkmcnt(2)
	s_nop 0
	v_lshlrev_b32_e32 v161, 16, v215
	v_lshlrev_b32_e32 v160, 16, v214
	s_waitcnt lgkmcnt(0)
	v_lshlrev_b32_e32 v163, 16, v217
	v_lshlrev_b32_e32 v162, 16, v216
	v_pk_add_f32 v[160:161], v[160:161], v[166:167] neg_lo:[0,1] neg_hi:[0,1]
	v_pk_add_f32 v[162:163], v[162:163], v[168:169] neg_lo:[0,1] neg_hi:[0,1]
	v_mul_f32_e32 v166, v186, v160
	v_mul_f32_e32 v167, v187, v161
	v_cvt_pk_bf16_f32 v160, v160, v161
	v_mul_f32_e32 v168, v170, v162
	v_mul_f32_e32 v169, v171, v163
	v_cvt_pk_bf16_f32 v161, v162, v163
	ds_write_b64 v136, v[160:161]
	v_cvt_pk_bf16_f32 v160, v166, v167
	v_cvt_pk_bf16_f32 v161, v168, v169
	ds_write_b64 v137, v[160:161]
	ds_read_u16 v160, v142
	ds_read_u16 v161, v142 offset:144
	v_mul_f32_e32 v162, 0x3fb8aa3b, v213
	v_mfma_f32_16x16x32_bf16 v[152:155], v[178:181], v[182:185], v[152:155]
	global_load_dwordx4 v[32:35], v[232:233], off
	v_lshl_add_u64 v[232:233], v[232:233], 0, s[20:21]
	v_exp_f32_e32 v195, v162
	ds_read_u16 v162, v142 offset:288
	ds_read_u16 v163, v142 offset:432
	s_waitcnt lgkmcnt(2)
	v_lshlrev_b32_e32 v161, 16, v161
	v_mfma_f32_16x16x32_bf16 v[152:155], v[206:209], v[190:193], v[152:155]
	s_mov_b64 s[30:31], exec
	s_mov_b64 exec, s[4:5]
	global_load_dword v118, v[234:235], off
	s_mov_b64 exec, s[30:31]
	v_lshl_add_u64 v[234:235], v[234:235], 0, s[28:29]
	v_lshlrev_b32_e32 v160, 16, v160
	v_pk_add_f32 v[148:149], v[160:161], v[148:149] neg_lo:[0,1] neg_hi:[0,1]
	s_waitcnt lgkmcnt(0)
	v_lshlrev_b32_e32 v161, 16, v163
	v_lshlrev_b32_e32 v160, 16, v162
	v_mfma_f32_16x16x32_bf16 v[156:159], v[206:209], v[202:205], v[156:159]
	v_add_f32_e64 v150, v160, -v150
	v_add_f32_e64 v151, v161, -v151
	v_mul_f32_e32 v166, v186, v148
	v_mul_f32_e32 v167, v187, v149
	v_cvt_pk_bf16_f32 v148, v148, v149
	v_mul_f32_e32 v160, v170, v150
	v_mul_f32_e32 v161, v171, v151
	v_cvt_pk_bf16_f32 v149, v150, v151
	ds_write_b64 v138, v[148:149]
	v_cvt_pk_bf16_f32 v148, v166, v167
	v_cvt_pk_bf16_f32 v149, v160, v161
	v_pk_mul_f32 v[152:153], v[152:153], v[210:211]
	v_pk_mul_f32 v[154:155], v[154:155], v[194:195]
	ds_write_b64 v139, v[148:149]
	s_waitcnt lgkmcnt(0)
	s_barrier
	ds_read_b128 v[148:151], v128
	ds_read_b128 v[160:163], v128 offset:64
	ds_read_b128 v[166:169], v129
	ds_read_b128 v[170:173], v129 offset:64
	ds_read_b128 v[174:177], v129 offset:2304
	ds_read_b128 v[178:181], v129 offset:2368
	ds_read_b128 v[182:185], v130 offset:52224
	ds_read_b128 v[186:189], v130 offset:52288
	s_waitcnt lgkmcnt(5)
	v_mfma_f32_16x16x32_bf16 v[152:155], v[148:151], v[166:169], v[152:155]
	v_mul_f32_e64 v156, v156, v210
	v_mul_f32_e64 v157, v157, v211
	v_pk_mul_f32 v[158:159], v[158:159], v[194:195]
	v_exp_f32_e32 v206, v147
	ds_read_b128 v[166:169], v143
	ds_read_b128 v[190:193], v143 offset:64
	s_waitcnt lgkmcnt(5)
	v_mfma_f32_16x16x32_bf16 v[148:151], v[148:151], v[174:177], v[156:159]
	s_nop 2
	ds_read_b128 v[156:159], v143 offset:2304
	ds_read_b128 v[174:177], v143 offset:2368
	ds_read_b128 v[194:197], v143 offset:4608
	ds_read_b128 v[198:201], v143 offset:4672
	v_pk_mul_f32 v[82:83], v[82:83], v[206:207] op_sel_hi:[1,0]
	v_pk_mul_f32 v[80:81], v[80:81], v[206:207] op_sel_hi:[1,0]
	v_mfma_f32_16x16x32_bf16 v[152:155], v[160:163], v[170:173], v[152:155]
	global_load_dwordx4 v[12:15], v[222:223], off
	v_lshl_add_u64 v[222:223], v[222:223], 0, s[20:21]
	ds_read_b128 v[170:173], v143 offset:6912
	ds_read_b128 v[202:205], v143 offset:6976
	v_pk_mul_f32 v[70:71], v[70:71], v[206:207] op_sel_hi:[1,0]
	v_pk_mul_f32 v[68:69], v[68:69], v[206:207] op_sel_hi:[1,0]
	s_waitcnt lgkmcnt(10)
	v_mfma_f32_16x16x32_bf16 v[148:151], v[160:163], v[178:181], v[148:151]
	v_mul_f32_e64 v78, v78, v206
	v_mul_f32_e64 v79, v79, v206
	v_pk_mul_f32 v[76:77], v[76:77], v[206:207] op_sel_hi:[1,0]
	v_pk_mul_f32 v[74:75], v[74:75], v[206:207] op_sel_hi:[1,0]
	s_waitcnt lgkmcnt(7)
	v_mfma_f32_16x16x32_bf16 v[80:83], v[182:185], v[166:169], v[80:83]
	v_mul_f32_e64 v72, v72, v206
	v_mul_f32_e64 v73, v73, v206
	v_cvt_pk_bf16_f32 v147, v152, s0
	ds_write_b16 v144, v147
	s_waitcnt lgkmcnt(6)
	v_mfma_f32_16x16x32_bf16 v[68:71], v[182:185], v[156:159], v[68:71]
	global_load_dwordx4 v[24:27], v[228:229], off
	v_lshl_add_u64 v[228:229], v[228:229], 0, s[20:21]
	v_cvt_pk_bf16_f32 v147, v153, s0
	ds_write_b16 v144, v147 offset:144
	s_waitcnt lgkmcnt(3)
	v_mfma_f32_16x16x32_bf16 v[156:159], v[182:185], v[170:173], v[76:79]
	s_nop 2
	v_cvt_pk_bf16_f32 v76, v154, s0
	v_mfma_f32_16x16x32_bf16 v[72:75], v[182:185], v[194:197], v[72:75]
	ds_write_b16 v144, v76 offset:288
	v_cvt_pk_bf16_f32 v76, v155, s0
	ds_write_b16 v144, v76 offset:432
	v_cvt_pk_bf16_f32 v76, v148, s0
	v_mfma_f32_16x16x32_bf16 v[80:83], v[186:189], v[190:193], v[80:83]
	ds_write_b16 v145, v76
	v_mfma_f32_16x16x32_bf16 v[76:79], v[186:189], v[174:177], v[68:71]
	global_load_dwordx4 v[28:31], v[230:231], off
	v_lshl_add_u64 v[230:231], v[230:231], 0, s[26:27]
	s_nop 2
	v_cvt_pk_bf16_f32 v68, v149, s0
	ds_write_b16 v145, v68 offset:144
	v_cvt_pk_bf16_f32 v68, v150, s0
	v_mfma_f32_16x16x32_bf16 v[72:75], v[186:189], v[198:201], v[72:75]
	ds_write_b16 v145, v68 offset:288
	v_cvt_pk_bf16_f32 v68, v151, s0
	ds_write_b16 v145, v68 offset:432
	s_waitcnt lgkmcnt(8)
	v_mfma_f32_16x16x32_bf16 v[68:71], v[186:189], v[202:205], v[156:159]
	v_cvt_pk_bf16_f32 v148, v80, v81
	v_cvt_pk_bf16_f32 v149, v82, v83
	ds_write_b64 v146, v[148:149] offset:34816
	v_cvt_pk_bf16_f32 v148, v76, v77
	v_cvt_pk_bf16_f32 v149, v78, v79
	ds_write_b64 v146, v[148:149] offset:39168
	v_cvt_pk_bf16_f32 v148, v72, v73
	v_cvt_pk_bf16_f32 v149, v74, v75
	ds_write_b64 v146, v[148:149] offset:43520
	v_cvt_pk_bf16_f32 v148, v68, v69
	v_cvt_pk_bf16_f32 v149, v70, v71
	s_cselect_b64 s[0:1], -1, 0
	s_cmpk_gt_u32 s10, 0x7e
	ds_write_b64 v146, v[148:149] offset:47872
	s_cbranch_scc1 .LBB0_537
	s_waitcnt vmcnt(13)
	ds_write_b128 v86, v[36:39]
	ds_write_b128 v86, v[40:43] offset:17408
	ds_write_b128 v88, v[48:51]
	ds_write_b128 v88, v[52:55] offset:17408
	ds_write_b128 v87, v[64:67]
	s_and_saveexec_b64 s[8:9], s[4:5]
	ds_write_b32 v135, v84
	s_or_b64 exec, exec, s[8:9]

.LBB0_541:
	s_waitcnt vmcnt(12)
	ds_write_b128 v89, v[44:47] offset:52224
	ds_write_b128 v119, v[56:59] offset:52224
	ds_write_b128 v120, v[60:63]
	s_branch .LBB0_524
.Lgdn_exit:
	s_waitcnt vmcnt(0)
	s_branch .LBB0_409
.LBB0_544:
	s_waitcnt vmcnt(0)
	s_waitcnt lgkmcnt(0)
	s_barrier
	s_mov_b64 s[0:1], exec
	v_readlane_b32 s2, v250, 1
	v_readlane_b32 s3, v250, 2
	v_readlane_b32 s54, v250, 41
	s_and_b64 s[2:3], s[0:1], s[2:3]
	v_readlane_b32 s53, v250, 0
	v_readlane_b32 s55, v250, 42
	s_mov_b64 exec, s[2:3]
	s_cbranch_execz .LBB0_596
	s_add_i32 s3, 0, 0x22c00
	v_mov_b32_e32 v0, s3
	s_getreg_b32 s2, hwreg(HW_REG_XCC_ID, 0, 4)
	s_waitcnt vmcnt(0) expcnt(0) lgkmcnt(0)
	ds_read_b32 v2, v0
	s_add_i32 s3, 0, 0x22c04
	v_mov_b32_e32 v0, s3
	ds_read_b32 v0, v0
	s_and_b32 s2, s2, 15
	s_waitcnt lgkmcnt(1)
	v_cmp_ne_u32_e32 vcc, 0, v2
	s_cbranch_vccnz .LBB0_560
	s_add_u32 s4, s82, 0x2a160200
	s_addc_u32 s5, s83, 0
	s_add_u32 s6, s82, 0x2a160400
	s_addc_u32 s7, s83, 0
	s_add_u32 s8, s82, 0x2a160500
	s_addc_u32 s9, s83, 0
	s_add_u32 s10, s82, 0x2a160600
	s_addc_u32 s11, s83, 0
	s_add_u32 s12, s82, 0x2a160700
	s_addc_u32 s13, s83, 0
	s_add_u32 s14, s82, 0x2a160800
	s_addc_u32 s15, s83, 0
	s_add_u32 s16, s82, 0x2a160900
	s_addc_u32 s17, s83, 0
	s_add_u32 s18, s82, 0x2a160a00
	s_addc_u32 s19, s83, 0
	s_add_u32 s20, s82, 0x2a160b00
	s_addc_u32 s21, s83, 0
	s_add_u32 s22, s82, 0x2a160c00
	s_addc_u32 s23, s83, 0
	s_add_u32 s24, s82, 0x2a160d00
	s_addc_u32 s25, s83, 0
	s_add_u32 s26, s82, 0x2a160e00
	s_addc_u32 s27, s83, 0
	s_add_u32 s28, s82, 0x2a160f00
	s_addc_u32 s29, s83, 0
	s_add_u32 s30, s82, 0x2a161000
	s_addc_u32 s31, s83, 0
	s_add_u32 s34, s82, 0x2a161100
	s_addc_u32 s35, s83, 0
	s_add_u32 s36, s82, 0x2a161200
	v_readlane_b32 s3, v250, 35
	s_addc_u32 s37, s83, 0
	s_mul_i32 s3, s55, s3
	s_add_u32 s38, s82, 0x2a161300
	s_mul_i32 s3, s3, s54
	s_addc_u32 s39, s83, 0
	s_mov_b32 s33, 1
	v_mov_b32_e32 v16, 0
	s_branch .LBB0_548
